# h3 + software-pipelined row loads in bf16 norm loops (norm_phase_b, norm_panels)
# baseline (speedup 1.0000x reference)
; __device__ __forceinline__ float bflo(unsigned w) { return __uint_as_float(w << 16); }
; __device__ __forceinline__ float bfhi(unsigned w) { return __uint_as_float(w & 0xffff0000u); }
; #define NORM_B_LOAD_MOD(b) f32x4 scv[2][2], shv[2][2]; _Pragma("unroll") for (int j = 0; j < 2; ++j) _Pragma("unroll") for (int n = 0; n < 2; ++n) { \
;         scv[j][n] = *(const f32x4*)(scale + (size_t)(b) * 6144 + 8 * lane + 512 * j + 4 * n) + 1.0f; shv[j][n] = *(const f32x4*)(shift + (size_t)(b) * 6144 + 8 * lane + 512 * j + 4 * n); }
; template <int R>
; __device__ __forceinline__ void norm_rows_b(const bf16* xrow, bf16* hrow, const f32x4 (&gv)[2][2], const f32x4 (&scv)[2][2], const f32x4 (&shv)[2][2], int lane) {
;     u32x4 w[R][2];
; #pragma unroll
;     for (int q = 0; q < R; ++q)
; #pragma unroll
;         for (int j = 0; j < 2; ++j) w[q][j] = *(const u32x4*)(xrow + (size_t)q * 1024 + 8 * lane + 512 * j);
;     f32x4 v[R][2][2]; float ssq[R];
; #pragma unroll
;     for (int q = 0; q < R; ++q) { float s_ = 0.f;
; #pragma unroll
;         for (int j = 0; j < 2; ++j) { const u32x4 ww = w[q][j];
;             v[q][j][0] = (f32x4){bflo(ww.x), bfhi(ww.x), bflo(ww.y), bfhi(ww.y)}; v[q][j][1] = (f32x4){bflo(ww.z), bfhi(ww.z), bflo(ww.w), bfhi(ww.w)};
; #pragma unroll
;             for (int n = 0; n < 2; ++n) s_ += (v[q][j][n].x * v[q][j][n].x + v[q][j][n].y * v[q][j][n].y) + (v[q][j][n].z * v[q][j][n].z + v[q][j][n].w * v[q][j][n].w); }
;         ssq[q] = s_; }
; __device__ __forceinline__ void norm_phase_b(const bf16* xb, const float* gain, const float* shift, const float* scale, bf16* H, int bid, int ngw) {
;     ...
;     for (int slab = gw; slab < TOK / 32; slab += ngw) {
;         const int row0 = slab * 32;
;         NORM_B_LOAD_MOD(row0 >> 11)
;         for (int r = 0; r < 32; r += 4) norm_rows_b<4>(xb + (size_t)(row0 + r) * 1024, H + (size_t)(row0 + r) * 1024, gv, scv, shv, lane);
.LBB0_181:
	s_ashr_i32 s3, s6, 6
	v_mad_i64_i32 v[18:19], s[0:1], s3, v252, v[52:53]
	flat_load_dwordx4 v[34:37], v[18:19]
	flat_load_dwordx4 v[38:41], v[18:19] offset:16
	v_mad_i64_i32 v[30:31], s[0:1], s3, v252, v[50:51]
	flat_load_dwordx4 v[42:45], v[18:19] offset:2048
	flat_load_dwordx4 v[46:49], v[18:19] offset:2064
	s_nop 0
	flat_load_dwordx4 v[18:21], v[30:31]
	flat_load_dwordx4 v[22:25], v[30:31] offset:16
	flat_load_dwordx4 v[26:29], v[30:31] offset:2048
	s_nop 0
	flat_load_dwordx4 v[30:33], v[30:31] offset:2064
	s_ashr_i32 s3, s2, 31
	s_lshl_b64 s[0:1], s[2:3], 11
	v_lshl_add_u64 v[56:57], v[54:55], 0, s[0:1]
	s_mov_b32 s3, -4
	s_mov_b64 s[12:13], 0x2000
	v_add_co_u32_e32 v146, vcc, 0xffffe000, v56
	s_nop 1
	v_addc_co_u32_e32 v147, vcc, -1, v57, vcc
	global_load_dwordx4 v[150:153], v[146:147], off offset:1024
	global_load_dwordx4 v[154:157], v[146:147], off offset:2048
	global_load_dwordx4 v[158:161], v[146:147], off offset:3072
	global_load_dwordx4 v[162:165], v[56:57], off offset:-4096
	global_load_dwordx4 v[166:169], v[56:57], off offset:-3072
	global_load_dwordx4 v[170:173], v[56:57], off offset:-2048
	global_load_dwordx4 v[174:177], v[56:57], off offset:-1024
	global_load_dwordx4 v[178:181], v[56:57], off
	s_waitcnt vmcnt(0) lgkmcnt(0)
	v_pk_add_f32 v[66:67], v[44:45], 1.0 op_sel_hi:[1,0]
	v_pk_add_f32 v[58:59], v[36:37], 1.0 op_sel_hi:[1,0]
	v_pk_add_f32 v[60:61], v[34:35], 1.0 op_sel_hi:[1,0]
	v_pk_add_f32 v[62:63], v[40:41], 1.0 op_sel_hi:[1,0]
	v_pk_add_f32 v[64:65], v[38:39], 1.0 op_sel_hi:[1,0]
	v_pk_add_f32 v[68:69], v[42:43], 1.0 op_sel_hi:[1,0]
	v_pk_add_f32 v[70:71], v[48:49], 1.0 op_sel_hi:[1,0]
	v_pk_add_f32 v[72:73], v[46:47], 1.0 op_sel_hi:[1,0]
.LBB0_182:
	v_mov_b64_e32 v[40:41], v[150:151]
	v_mov_b64_e32 v[42:43], v[152:153]
	v_mov_b64_e32 v[44:45], v[154:155]
	v_mov_b64_e32 v[46:47], v[156:157]
	v_mov_b64_e32 v[74:75], v[158:159]
	v_mov_b64_e32 v[76:77], v[160:161]
	v_mov_b64_e32 v[78:79], v[162:163]
	v_mov_b64_e32 v[80:81], v[164:165]
	v_mov_b64_e32 v[82:83], v[166:167]
	v_mov_b64_e32 v[84:85], v[168:169]
	v_mov_b64_e32 v[88:89], v[170:171]
	v_mov_b64_e32 v[90:91], v[172:173]
	v_mov_b64_e32 v[96:97], v[174:175]
	v_mov_b64_e32 v[98:99], v[176:177]
	v_mov_b64_e32 v[100:101], v[178:179]
	v_mov_b64_e32 v[102:103], v[180:181]
	s_cmp_gt_i32 s3, 23
	s_cbranch_scc1 .Lnp_skip_182
	v_lshl_add_u64 v[146:147], v[56:57], 0, s[12:13]
	global_load_dwordx4 v[150:153], v[56:57], off offset:1024
	global_load_dwordx4 v[154:157], v[56:57], off offset:2048
	global_load_dwordx4 v[158:161], v[56:57], off offset:3072
	global_load_dwordx4 v[162:165], v[146:147], off offset:-4096
	global_load_dwordx4 v[166:169], v[146:147], off offset:-3072
	global_load_dwordx4 v[170:173], v[146:147], off offset:-2048
	global_load_dwordx4 v[174:177], v[146:147], off offset:-1024
	global_load_dwordx4 v[178:181], v[146:147], off
.Lnp_skip_182:
	s_add_i32 s3, s3, 4
	s_cmp_gt_u32 s3, 27
	v_and_b32_e32 v105, 0xffff0000, v43
	v_and_b32_e32 v104, 0xffff0000, v42
	v_lshlrev_b32_e32 v34, 16, v40
	v_and_b32_e32 v35, 0xffff0000, v40
	v_lshlrev_b32_e32 v40, 16, v41
	v_lshlrev_b32_e32 v39, 16, v43
	v_lshlrev_b32_e32 v38, 16, v42
	v_lshlrev_b32_e32 v114, 16, v78
	v_and_b32_e32 v115, 0xffff0000, v78
	v_lshlrev_b32_e32 v116, 16, v79
	v_and_b32_e32 v117, 0xffff0000, v79
	v_mul_f32_e32 v0, v34, v34
	v_and_b32_e32 v41, 0xffff0000, v41
	v_mov_b32_e32 v120, v39
	v_mov_b32_e32 v121, v105
	v_lshlrev_b32_e32 v36, 16, v46
	v_and_b32_e32 v37, 0xffff0000, v46
	v_lshlrev_b32_e32 v108, 16, v44
	v_and_b32_e32 v109, 0xffff0000, v44
	v_lshlrev_b32_e32 v112, 16, v45
	v_and_b32_e32 v123, 0xffff0000, v77
	v_and_b32_e32 v122, 0xffff0000, v76
	v_and_b32_e32 v113, 0xffff0000, v45
	v_lshlrev_b32_e32 v49, 16, v77
	v_lshlrev_b32_e32 v48, 16, v76
	v_pk_mul_f32 v[134:135], v[122:123], v[122:123]
	v_lshlrev_b32_e32 v42, 16, v47
	v_and_b32_e32 v43, 0xffff0000, v47
	v_lshlrev_b32_e32 v44, 16, v74
	v_pk_fma_f32 v[134:135], v[48:49], v[48:49], v[134:135]
	v_and_b32_e32 v45, 0xffff0000, v74
	v_lshlrev_b32_e32 v106, 16, v75
	v_and_b32_e32 v107, 0xffff0000, v75
	v_lshlrev_b32_e32 v46, 16, v80
	v_and_b32_e32 v47, 0xffff0000, v80
	v_lshlrev_b32_e32 v110, 16, v81
	v_and_b32_e32 v111, 0xffff0000, v81
	v_lshlrev_b32_e32 v79, 16, v85
	v_lshlrev_b32_e32 v78, 16, v84
	v_and_b32_e32 v125, 0xffff0000, v85
	v_and_b32_e32 v124, 0xffff0000, v84
	v_lshlrev_b32_e32 v86, 16, v88
	v_and_b32_e32 v87, 0xffff0000, v88
	v_lshlrev_b32_e32 v94, 16, v89
	v_and_b32_e32 v95, 0xffff0000, v89
	v_lshlrev_b32_e32 v84, 16, v96
	v_and_b32_e32 v85, 0xffff0000, v96
	v_lshlrev_b32_e32 v92, 16, v97
	v_and_b32_e32 v93, 0xffff0000, v97
	v_lshlrev_b32_e32 v88, 16, v102
	v_and_b32_e32 v89, 0xffff0000, v102
	v_lshlrev_b32_e32 v96, 16, v103
	v_and_b32_e32 v97, 0xffff0000, v103
	v_pk_mul_f32 v[102:103], v[104:105], v[104:105]
	v_lshlrev_b32_e32 v74, 16, v82
	v_pk_fma_f32 v[102:103], v[38:39], v[38:39], v[102:103]
	v_mov_b32_e32 v39, v104
	v_pk_fma_f32 v[104:105], v[34:35], v[34:35], v[0:1] op_sel_hi:[1,1,0]
	v_mul_f32_e32 v0, v40, v40
	v_pk_fma_f32 v[118:119], v[40:41], v[40:41], v[0:1] op_sel_hi:[1,1,0]
	v_pk_add_f32 v[102:103], v[102:103], v[102:103] op_sel_hi:[0,1]
	v_pk_add_f32 v[104:105], v[104:105], v[118:119]
	v_mul_f32_e32 v102, v37, v37
	v_mul_f32_e32 v104, v36, v36
	v_mul_f32_e32 v0, v108, v108
	v_pk_add_f32 v[102:103], v[104:105], v[102:103]
	v_pk_fma_f32 v[104:105], v[108:109], v[108:109], v[0:1] op_sel_hi:[1,1,0]
	v_mul_f32_e32 v0, v112, v112
	v_mov_b32_e32 v118, v49
	v_mov_b32_e32 v119, v123
	v_mov_b32_e32 v49, v122
	v_pk_fma_f32 v[122:123], v[112:113], v[112:113], v[0:1] op_sel_hi:[1,1,0]
	v_mul_f32_e32 v104, v42, v42
; __device__ __forceinline__ float shx(float v, int m, int lane) { return __int_as_float(__builtin_amdgcn_ds_bpermute((lane ^ m) << 2, __float_as_int(v))); }
; __device__ __forceinline__ float bflo(unsigned w) { return __uint_as_float(w << 16); }
; __device__ __forceinline__ float bfhi(unsigned w) { return __uint_as_float(w & 0xffff0000u); }
; template <int R>
; __device__ __forceinline__ void norm_rows_b(const bf16* xrow, bf16* hrow, const f32x4 (&gv)[2][2], const f32x4 (&scv)[2][2], const f32x4 (&shv)[2][2], int lane) {
;     ...
;     for (int q = 0; q < R; ++q) { float s_ = 0.f;
; #pragma unroll
;         for (int j = 0; j < 2; ++j) { const u32x4 ww = w[q][j];
;             v[q][j][0] = (f32x4){bflo(ww.x), bfhi(ww.x), bflo(ww.y), bfhi(ww.y)}; v[q][j][1] = (f32x4){bflo(ww.z), bfhi(ww.z), bflo(ww.w), bfhi(ww.w)};
; #pragma unroll
;             for (int n = 0; n < 2; ++n) s_ += (v[q][j][n].x * v[q][j][n].x + v[q][j][n].y * v[q][j][n].y) + (v[q][j][n].z * v[q][j][n].z + v[q][j][n].w * v[q][j][n].w); }
;         ssq[q] = s_; }
; #pragma unroll
;     for (int o = 1; o < 64; o <<= 1)
; #pragma unroll
;         for (int q = 0; q < R; ++q) ssq[q] += shx(ssq[q], o, lane);
; #pragma unroll
;     for (int q = 0; q < R; ++q) { const float rstd = rsqrtf(ssq[q] * (1.0f / 1024.0f) + RMS_EPS);
	v_mul_f32_e32 v122, v43, v43
	v_mul_f32_e32 v0, v44, v44
	v_pk_add_f32 v[104:105], v[104:105], v[122:123]
	v_pk_fma_f32 v[122:123], v[44:45], v[44:45], v[0:1] op_sel_hi:[1,1,0]
	v_mul_f32_e32 v0, v106, v106
	v_pk_fma_f32 v[136:137], v[106:107], v[106:107], v[0:1] op_sel_hi:[1,1,0]
	v_mul_f32_e32 v0, v114, v114
	v_pk_add_f32 v[122:123], v[122:123], v[136:137]
	v_pk_add_f32 v[136:137], v[102:103], v[104:105]
	v_pk_mul_f32 v[104:105], v[124:125], v[124:125]
	v_mul_f32_e32 v122, v46, v46
	v_pk_fma_f32 v[138:139], v[78:79], v[78:79], v[104:105]
	v_pk_add_f32 v[104:105], v[134:135], v[134:135] op_sel_hi:[0,1]
	v_mul_f32_e32 v104, v47, v47
	v_pk_add_f32 v[104:105], v[122:123], v[104:105]
	v_pk_fma_f32 v[122:123], v[114:115], v[114:115], v[0:1] op_sel_hi:[1,1,0]
	v_mul_f32_e32 v0, v116, v116
	v_mov_b32_e32 v102, v79
	v_mov_b32_e32 v103, v125
	v_mov_b32_e32 v79, v124
	v_pk_fma_f32 v[124:125], v[116:117], v[116:117], v[0:1] op_sel_hi:[1,1,0]
	v_and_b32_e32 v75, 0xffff0000, v82
	v_lshlrev_b32_e32 v80, 16, v83
	v_mul_f32_e32 v122, v110, v110
	v_mul_f32_e32 v124, v111, v111
	v_mul_f32_e32 v0, v74, v74
	v_and_b32_e32 v81, 0xffff0000, v83
	v_pk_add_f32 v[122:123], v[122:123], v[124:125]
	v_pk_fma_f32 v[124:125], v[74:75], v[74:75], v[0:1] op_sel_hi:[1,1,0]
	v_mul_f32_e32 v0, v80, v80
	v_and_b32_e32 v133, 0xffff0000, v99
	v_and_b32_e32 v132, 0xffff0000, v98
	v_pk_fma_f32 v[134:135], v[80:81], v[80:81], v[0:1] op_sel_hi:[1,1,0]
	v_lshlrev_b32_e32 v76, 16, v90
	v_and_b32_e32 v77, 0xffff0000, v90
	v_lshlrev_b32_e32 v82, 16, v91
	v_and_b32_e32 v83, 0xffff0000, v91
	v_lshlrev_b32_e32 v91, 16, v99
	v_lshlrev_b32_e32 v90, 16, v98
	v_pk_add_f32 v[124:125], v[124:125], v[134:135]
	v_pk_mul_f32 v[134:135], v[132:133], v[132:133]
	v_pk_add_f32 v[122:123], v[104:105], v[122:123]
	v_mov_b32_e32 v104, v91
	v_mov_b32_e32 v105, v133
	v_pk_fma_f32 v[134:135], v[90:91], v[90:91], v[134:135]
	v_mov_b32_e32 v91, v132
	v_pk_add_f32 v[132:133], v[138:139], v[138:139] op_sel_hi:[0,1]
	v_mul_f32_e32 v124, v76, v76
	v_mul_f32_e32 v132, v77, v77
	v_mul_f32_e32 v0, v86, v86
	v_pk_add_f32 v[124:125], v[124:125], v[132:133]
	v_pk_fma_f32 v[132:133], v[86:87], v[86:87], v[0:1] op_sel_hi:[1,1,0]
	v_mul_f32_e32 v0, v94, v94
	v_pk_fma_f32 v[138:139], v[94:95], v[94:95], v[0:1] op_sel_hi:[1,1,0]
	v_mul_f32_e32 v132, v82, v82
	v_mul_f32_e32 v138, v83, v83
	v_mul_f32_e32 v0, v84, v84
	v_lshlrev_b32_e32 v98, 16, v100
	v_pk_add_f32 v[132:133], v[132:133], v[138:139]
	v_pk_fma_f32 v[138:139], v[84:85], v[84:85], v[0:1] op_sel_hi:[1,1,0]
	v_mul_f32_e32 v0, v92, v92
	v_and_b32_e32 v99, 0xffff0000, v100
	v_lshlrev_b32_e32 v100, 16, v101
	v_pk_fma_f32 v[140:141], v[92:93], v[92:93], v[0:1] op_sel_hi:[1,1,0]
	v_mul_f32_e32 v0, v98, v98
	v_and_b32_e32 v101, 0xffff0000, v101
	v_pk_add_f32 v[138:139], v[138:139], v[140:141]
	v_mov_b32_e32 v141, v136
	v_mov_b32_e32 v140, v122
	v_mov_b32_e32 v136, v123
	v_pk_add_f32 v[122:123], v[124:125], v[132:133]
	v_pk_fma_f32 v[124:125], v[98:99], v[98:99], v[0:1] op_sel_hi:[1,1,0]
	v_mul_f32_e32 v0, v100, v100
	v_pk_fma_f32 v[132:133], v[100:101], v[100:101], v[0:1] op_sel_hi:[1,1,0]
	v_pk_add_f32 v[134:135], v[134:135], v[134:135] op_sel_hi:[0,1]
	v_mul_f32_e32 v124, v96, v96
	v_mul_f32_e32 v132, v97, v97
	v_mul_f32_e32 v138, v88, v88
	v_mul_f32_e32 v134, v89, v89
	v_pk_add_f32 v[124:125], v[124:125], v[132:133]
	v_pk_add_f32 v[134:135], v[138:139], v[134:135]
	v_pk_add_f32 v[132:133], v[140:141], v[136:137]
	v_pk_add_f32 v[124:125], v[134:135], v[124:125]
	v_mov_b32_e32 v135, v122
	v_mov_b32_e32 v134, v124
	v_mov_b32_e32 v122, v125
	ds_bpermute_b32 v125, v126, v133
	ds_bpermute_b32 v124, v126, v132
	v_pk_add_f32 v[122:123], v[134:135], v[122:123]
	s_waitcnt lgkmcnt(0)
	v_pk_add_f32 v[124:125], v[132:133], v[124:125]
	ds_bpermute_b32 v133, v126, v123
	ds_bpermute_b32 v132, v126, v122
	s_waitcnt lgkmcnt(0)
	v_pk_add_f32 v[122:123], v[122:123], v[132:133]
	ds_bpermute_b32 v133, v127, v125
	ds_bpermute_b32 v132, v127, v124
	s_waitcnt lgkmcnt(0)
	v_pk_add_f32 v[124:125], v[124:125], v[132:133]
	ds_bpermute_b32 v133, v127, v123
	ds_bpermute_b32 v132, v127, v122
	s_waitcnt lgkmcnt(0)
	v_pk_add_f32 v[122:123], v[122:123], v[132:133]
	ds_bpermute_b32 v133, v128, v125
	ds_bpermute_b32 v132, v128, v124
	s_waitcnt lgkmcnt(0)
	v_pk_add_f32 v[124:125], v[124:125], v[132:133]
	ds_bpermute_b32 v133, v128, v123
	ds_bpermute_b32 v132, v128, v122
	s_waitcnt lgkmcnt(0)
	v_pk_add_f32 v[122:123], v[122:123], v[132:133]
	ds_bpermute_b32 v133, v129, v125
	ds_bpermute_b32 v132, v129, v124
	s_waitcnt lgkmcnt(0)
	v_pk_add_f32 v[124:125], v[124:125], v[132:133]
	ds_bpermute_b32 v133, v129, v123
	ds_bpermute_b32 v132, v129, v122
	s_waitcnt lgkmcnt(0)
	v_pk_add_f32 v[122:123], v[122:123], v[132:133]
	ds_bpermute_b32 v133, v130, v125
	ds_bpermute_b32 v132, v130, v124
	s_waitcnt lgkmcnt(0)
	v_pk_add_f32 v[124:125], v[124:125], v[132:133]
	ds_bpermute_b32 v133, v130, v123
	ds_bpermute_b32 v132, v130, v122
	s_waitcnt lgkmcnt(0)
	v_pk_add_f32 v[122:123], v[122:123], v[132:133]
	ds_bpermute_b32 v133, v131, v125
	ds_bpermute_b32 v132, v131, v124
	s_waitcnt lgkmcnt(0)
	v_pk_add_f32 v[124:125], v[124:125], v[132:133]
	v_mov_b64_e32 v[132:133], s[4:5]
	v_pk_fma_f32 v[124:125], v[124:125], s[86:87], v[132:133] op_sel_hi:[1,0,0]
	s_nop 0
	v_mul_f32_e32 v0, 0x4b800000, v124
	v_cmp_gt_f32_e32 vcc, s87, v124
	v_mul_f32_e32 v134, 0x4b800000, v125
	v_cmp_gt_f32_e64 s[8:9], s87, v125
	v_cndmask_b32_e32 v140, v124, v0, vcc
	ds_bpermute_b32 v124, v131, v122
	v_cndmask_b32_e64 v134, v125, v134, s[8:9]
	ds_bpermute_b32 v125, v131, v123
	s_waitcnt lgkmcnt(0)
; __device__ __forceinline__ unsigned cvt_pk_bf16(float lo, float hi) { f32x2_t v = {lo, hi}; bf16x2_t b = __builtin_convertvector(v, bf16x2_t); return __builtin_bit_cast(unsigned, b); }
; template <int R>
; __device__ __forceinline__ void norm_rows_b(const bf16* xrow, bf16* hrow, const f32x4 (&gv)[2][2], const f32x4 (&scv)[2][2], const f32x4 (&shv)[2][2], int lane) {
;     ...
;     for (int q = 0; q < R; ++q) { const float rstd = rsqrtf(ssq[q] * (1.0f / 1024.0f) + RMS_EPS);
; #pragma unroll
;         for (int j = 0; j < 2; ++j) { const f32x4 y0 = v[q][j][0] * rstd * gv[j][0] * scv[j][0] + shv[j][0], y1 = v[q][j][1] * rstd * gv[j][1] * scv[j][1] + shv[j][1];
;             u32x4 o_; o_.x = cvt_pk_bf16(y0.x, y0.y); o_.y = cvt_pk_bf16(y0.z, y0.w); o_.z = cvt_pk_bf16(y1.x, y1.y); o_.w = cvt_pk_bf16(y1.z, y1.w);
;             *(u32x4*)(hrow + (size_t)q * 1024 + 8 * lane + 512 * j) = o_; } }
	v_pk_add_f32 v[122:123], v[122:123], v[124:125]
	s_nop 0
	v_pk_fma_f32 v[122:123], v[122:123], s[86:87], v[132:133] op_sel_hi:[1,0,0]
	s_nop 0
	v_mul_f32_e32 v124, 0x4b800000, v122
	v_cmp_gt_f32_e64 s[0:1], s87, v122
	v_mul_f32_e32 v0, 0x4b800000, v123
	v_cmp_gt_f32_e64 s[4:5], s87, v123
	v_cndmask_b32_e64 v132, v122, v124, s[0:1]
	v_rsq_f32_e32 v122, v134
	v_cndmask_b32_e64 v0, v123, v0, s[4:5]
	v_rsq_f32_e32 v0, v0
	v_mul_f32_e32 v123, 0x45800000, v122
	v_cndmask_b32_e64 v122, v122, v123, s[8:9]
	v_pk_mul_f32 v[138:139], v[122:123], v[36:37] op_sel_hi:[0,1]
	v_rsq_f32_e32 v36, v140
	v_pk_mul_f32 v[40:41], v[122:123], v[40:41] op_sel_hi:[0,1]
	v_pk_mul_f32 v[34:35], v[122:123], v[34:35] op_sel_hi:[0,1]
	v_pk_mul_f32 v[136:137], v[122:123], v[108:109] op_sel_hi:[0,1]
	v_mul_f32_e32 v37, 0x45800000, v36
	v_cndmask_b32_e32 v36, v36, v37, vcc
	v_add_co_u32_e32 v108, vcc, s77, v56
	v_pk_mul_f32 v[134:135], v[122:123], v[120:121] op_sel_hi:[0,1]
	v_pk_mul_f32 v[38:39], v[122:123], v[38:39] op_sel_hi:[0,1]
	v_pk_mul_f32 v[112:113], v[122:123], v[112:113] op_sel_hi:[0,1]
	v_pk_mul_f32 v[42:43], v[122:123], v[42:43] op_sel_hi:[0,1]
	v_pk_mul_f32 v[140:141], v[36:37], v[106:107] op_sel_hi:[0,1]
	v_pk_mul_f32 v[142:143], v[36:37], v[44:45] op_sel_hi:[0,1]
	v_pk_mul_f32 v[120:121], v[36:37], v[118:119] op_sel_hi:[0,1]
	v_pk_mul_f32 v[44:45], v[36:37], v[48:49] op_sel_hi:[0,1]
	v_pk_mul_f32 v[122:123], v[36:37], v[116:117] op_sel_hi:[0,1]
	v_pk_mul_f32 v[124:125], v[36:37], v[114:115] op_sel_hi:[0,1]
	v_pk_mul_f32 v[106:107], v[36:37], v[110:111] op_sel_hi:[0,1]
	v_pk_mul_f32 v[48:49], v[36:37], v[46:47] op_sel_hi:[0,1]
	v_pk_mul_f32 v[34:35], v[6:7], v[34:35]
	v_pk_mul_f32 v[36:37], v[8:9], v[40:41]
	v_addc_co_u32_e32 v109, vcc, -1, v57, vcc
	v_pk_fma_f32 v[36:37], v[58:59], v[36:37], v[20:21]
	v_pk_fma_f32 v[34:35], v[60:61], v[34:35], v[18:19]
	v_add_co_u32_e32 v110, vcc, s92, v56
	v_cvt_pk_bf16_f32 v34, v34, v35
	v_cvt_pk_bf16_f32 v35, v36, v37
	v_pk_mul_f32 v[36:37], v[2:3], v[38:39]
	v_addc_co_u32_e32 v111, vcc, -1, v57, vcc
	v_pk_mul_f32 v[38:39], v[4:5], v[134:135]
	v_pk_mul_f32 v[40:41], v[14:15], v[136:137]
	v_pk_mul_f32 v[46:47], v[16:17], v[112:113]
	v_pk_fma_f32 v[36:37], v[64:65], v[36:37], v[22:23]
	v_pk_fma_f32 v[38:39], v[62:63], v[38:39], v[24:25]
	v_pk_fma_f32 v[46:47], v[66:67], v[46:47], v[28:29]
	v_pk_fma_f32 v[40:41], v[68:69], v[40:41], v[26:27]
	v_add_co_u32_e32 v114, vcc, s93, v56
	v_cvt_pk_bf16_f32 v36, v36, v37
	v_cvt_pk_bf16_f32 v37, v38, v39
	v_cvt_pk_bf16_f32 v38, v40, v41
	v_cvt_pk_bf16_f32 v39, v46, v47
	v_addc_co_u32_e32 v115, vcc, -1, v57, vcc
	v_pk_mul_f32 v[40:41], v[10:11], v[138:139]
	v_pk_mul_f32 v[42:43], v[12:13], v[42:43]
	v_pk_mul_f32 v[46:47], v[6:7], v[142:143]
	v_pk_fma_f32 v[40:41], v[72:73], v[40:41], v[30:31]
	v_add_co_u32_e32 v118, vcc, s66, v56
	v_pk_mul_f32 v[112:113], v[8:9], v[140:141]
	v_pk_fma_f32 v[42:43], v[70:71], v[42:43], v[32:33]
	v_pk_fma_f32 v[46:47], v[60:61], v[46:47], v[18:19]
	v_cvt_pk_bf16_f32 v40, v40, v41
	v_addc_co_u32_e32 v119, vcc, -1, v57, vcc
	v_pk_fma_f32 v[112:113], v[58:59], v[112:113], v[20:21]
	v_cvt_pk_bf16_f32 v41, v42, v43
	v_cvt_pk_bf16_f32 v42, v46, v47
	v_pk_mul_f32 v[46:47], v[4:5], v[120:121]
	v_pk_mul_f32 v[120:121], v[14:15], v[124:125]
	v_rsq_f32_e32 v124, v132
	v_cvt_pk_bf16_f32 v43, v112, v113
	v_add_co_u32_e32 v112, vcc, s67, v56
	v_pk_mul_f32 v[48:49], v[10:11], v[48:49]
	v_pk_mul_f32 v[106:107], v[12:13], v[106:107]
	v_addc_co_u32_e32 v113, vcc, -1, v57, vcc
	v_pk_fma_f32 v[48:49], v[72:73], v[48:49], v[30:31]
	v_pk_fma_f32 v[106:107], v[70:71], v[106:107], v[32:33]
	v_pk_mul_f32 v[44:45], v[2:3], v[44:45]
	v_add_co_u32_e32 v116, vcc, s7, v56
	v_pk_mul_f32 v[122:123], v[16:17], v[122:123]
	v_cvt_pk_bf16_f32 v48, v48, v49
	v_cvt_pk_bf16_f32 v49, v106, v107
	v_mul_f32_e32 v106, 0x45800000, v0
	v_pk_fma_f32 v[44:45], v[64:65], v[44:45], v[22:23]
	v_addc_co_u32_e32 v117, vcc, -1, v57, vcc
	v_pk_fma_f32 v[46:47], v[62:63], v[46:47], v[24:25]
	v_pk_fma_f32 v[122:123], v[66:67], v[122:123], v[28:29]
; __device__ __forceinline__ unsigned cvt_pk_bf16(float lo, float hi) { f32x2_t v = {lo, hi}; bf16x2_t b = __builtin_convertvector(v, bf16x2_t); return __builtin_bit_cast(unsigned, b); }
; #define NORM_B_LOAD_MOD(b) f32x4 scv[2][2], shv[2][2]; _Pragma("unroll") for (int j = 0; j < 2; ++j) _Pragma("unroll") for (int n = 0; n < 2; ++n) { \
;         scv[j][n] = *(const f32x4*)(scale + (size_t)(b) * 6144 + 8 * lane + 512 * j + 4 * n) + 1.0f; shv[j][n] = *(const f32x4*)(shift + (size_t)(b) * 6144 + 8 * lane + 512 * j + 4 * n); }
; template <int R>
; __device__ __forceinline__ void norm_rows_b(const bf16* xrow, bf16* hrow, const f32x4 (&gv)[2][2], const f32x4 (&scv)[2][2], const f32x4 (&shv)[2][2], int lane) {
;     ...
;     for (int q = 0; q < R; ++q) { const float rstd = rsqrtf(ssq[q] * (1.0f / 1024.0f) + RMS_EPS);
; #pragma unroll
;         for (int j = 0; j < 2; ++j) { const f32x4 y0 = v[q][j][0] * rstd * gv[j][0] * scv[j][0] + shv[j][0], y1 = v[q][j][1] * rstd * gv[j][1] * scv[j][1] + shv[j][1];
;             u32x4 o_; o_.x = cvt_pk_bf16(y0.x, y0.y); o_.y = cvt_pk_bf16(y0.z, y0.w); o_.z = cvt_pk_bf16(y1.x, y1.y); o_.w = cvt_pk_bf16(y1.z, y1.w);
;             *(u32x4*)(hrow + (size_t)q * 1024 + 8 * lane + 512 * j) = o_; } }
; __device__ __forceinline__ void norm_phase_b(const bf16* xb, const float* gain, const float* shift, const float* scale, bf16* H, int bid, int ngw) {
;     ...
;     for (int slab = gw; slab < TOK / 32; slab += ngw) {
;         const int row0 = slab * 32;
;         NORM_B_LOAD_MOD(row0 >> 11)
;         for (int r = 0; r < 32; r += 4) norm_rows_b<4>(xb + (size_t)(row0 + r) * 1024, H + (size_t)(row0 + r) * 1024, gv, scv, shv, lane);
	v_pk_fma_f32 v[120:121], v[68:69], v[120:121], v[26:27]
	v_mul_f32_e32 v107, 0x45800000, v124
	v_cndmask_b32_e64 v0, v0, v106, s[4:5]
	v_cvt_pk_bf16_f32 v44, v44, v45
	v_cvt_pk_bf16_f32 v45, v46, v47
	v_cvt_pk_bf16_f32 v46, v120, v121
	v_cvt_pk_bf16_f32 v47, v122, v123
	v_add_co_u32_e32 v120, vcc, s10, v56
	v_cndmask_b32_e64 v106, v124, v107, s[0:1]
	global_store_dwordx4 v[108:109], v[34:37], off
	global_store_dwordx4 v[110:111], v[38:41], off
	global_store_dwordx4 v[114:115], v[42:45], off
	global_store_dwordx4 v[118:119], v[46:49], off
	v_pk_mul_f32 v[34:35], v[0:1], v[80:81] op_sel_hi:[0,1]
	v_pk_mul_f32 v[36:37], v[0:1], v[74:75] op_sel_hi:[0,1]
	v_pk_mul_f32 v[38:39], v[0:1], v[102:103] op_sel_hi:[0,1]
	v_pk_mul_f32 v[40:41], v[0:1], v[78:79] op_sel_hi:[0,1]
	v_addc_co_u32_e32 v121, vcc, -1, v57, vcc
	v_pk_mul_f32 v[42:43], v[0:1], v[94:95] op_sel_hi:[0,1]
	v_pk_mul_f32 v[44:45], v[0:1], v[86:87] op_sel_hi:[0,1]
	v_pk_mul_f32 v[46:47], v[0:1], v[82:83] op_sel_hi:[0,1]
	v_pk_mul_f32 v[48:49], v[0:1], v[76:77] op_sel_hi:[0,1]
	v_pk_mul_f32 v[74:75], v[106:107], v[92:93] op_sel_hi:[0,1]
	v_pk_mul_f32 v[76:77], v[106:107], v[84:85] op_sel_hi:[0,1]
	v_pk_mul_f32 v[78:79], v[106:107], v[104:105] op_sel_hi:[0,1]
	v_pk_mul_f32 v[80:81], v[106:107], v[90:91] op_sel_hi:[0,1]
	v_pk_mul_f32 v[82:83], v[106:107], v[100:101] op_sel_hi:[0,1]
	v_pk_mul_f32 v[84:85], v[106:107], v[98:99] op_sel_hi:[0,1]
	v_pk_mul_f32 v[86:87], v[106:107], v[96:97] op_sel_hi:[0,1]
	v_pk_mul_f32 v[88:89], v[106:107], v[88:89] op_sel_hi:[0,1]
	v_pk_mul_f32 v[36:37], v[6:7], v[36:37]
	v_pk_mul_f32 v[34:35], v[8:9], v[34:35]
	v_pk_mul_f32 v[40:41], v[2:3], v[40:41]
	v_pk_mul_f32 v[38:39], v[4:5], v[38:39]
	v_add_co_u32_e32 v122, vcc, 0xd7800000, v56
	v_pk_mul_f32 v[44:45], v[14:15], v[44:45]
	v_pk_mul_f32 v[42:43], v[16:17], v[42:43]
	v_pk_mul_f32 v[48:49], v[10:11], v[48:49]
	v_pk_mul_f32 v[46:47], v[12:13], v[46:47]
	v_pk_mul_f32 v[76:77], v[6:7], v[76:77]
	v_pk_mul_f32 v[74:75], v[8:9], v[74:75]
	v_pk_mul_f32 v[80:81], v[2:3], v[80:81]
	v_pk_mul_f32 v[78:79], v[4:5], v[78:79]
	v_pk_mul_f32 v[84:85], v[14:15], v[84:85]
	v_pk_mul_f32 v[82:83], v[16:17], v[82:83]
	v_pk_mul_f32 v[88:89], v[10:11], v[88:89]
	v_pk_mul_f32 v[86:87], v[12:13], v[86:87]
	v_pk_fma_f32 v[90:91], v[58:59], v[34:35], v[20:21]
	v_pk_fma_f32 v[34:35], v[60:61], v[36:37], v[18:19]
	v_pk_fma_f32 v[38:39], v[62:63], v[38:39], v[24:25]
	v_pk_fma_f32 v[36:37], v[64:65], v[40:41], v[22:23]
	v_addc_co_u32_e32 v123, vcc, -1, v57, vcc
	v_lshl_add_u64 v[56:57], v[56:57], 0, s[12:13]
	s_mov_b32 s4, 0x358637bd
	v_pk_fma_f32 v[40:41], v[66:67], v[42:43], v[28:29]
	v_pk_fma_f32 v[42:43], v[68:69], v[44:45], v[26:27]
	v_pk_fma_f32 v[44:45], v[70:71], v[46:47], v[32:33]
	v_pk_fma_f32 v[46:47], v[72:73], v[48:49], v[30:31]
	v_pk_fma_f32 v[48:49], v[58:59], v[74:75], v[20:21]
	v_pk_fma_f32 v[74:75], v[60:61], v[76:77], v[18:19]
	v_pk_fma_f32 v[76:77], v[62:63], v[78:79], v[24:25]
	v_pk_fma_f32 v[78:79], v[64:65], v[80:81], v[22:23]
	v_pk_fma_f32 v[80:81], v[66:67], v[82:83], v[28:29]
	v_pk_fma_f32 v[82:83], v[68:69], v[84:85], v[26:27]
	v_pk_fma_f32 v[84:85], v[70:71], v[86:87], v[32:33]
	v_pk_fma_f32 v[86:87], v[72:73], v[88:89], v[30:31]
	v_cvt_pk_bf16_f32 v34, v34, v35
	v_cvt_pk_bf16_f32 v35, v90, v91
	v_cvt_pk_bf16_f32 v36, v36, v37
	v_cvt_pk_bf16_f32 v37, v38, v39
	v_cvt_pk_bf16_f32 v38, v42, v43
	v_cvt_pk_bf16_f32 v39, v40, v41
	v_cvt_pk_bf16_f32 v40, v46, v47
	v_cvt_pk_bf16_f32 v41, v44, v45
	v_cvt_pk_bf16_f32 v42, v74, v75
	v_cvt_pk_bf16_f32 v43, v48, v49
	v_cvt_pk_bf16_f32 v44, v78, v79
	v_cvt_pk_bf16_f32 v45, v76, v77
	v_cvt_pk_bf16_f32 v46, v82, v83
	v_cvt_pk_bf16_f32 v47, v80, v81
	v_cvt_pk_bf16_f32 v48, v86, v87
	v_cvt_pk_bf16_f32 v49, v84, v85
	global_store_dwordx4 v[112:113], v[34:37], off
	global_store_dwordx4 v[116:117], v[38:41], off
	global_store_dwordx4 v[120:121], v[42:45], off
	global_store_dwordx4 v[122:123], v[46:49], off
	s_waitcnt vmcnt(8)
	s_cbranch_scc0 .LBB0_182
	s_add_i32 s6, s6, s68
	s_add_i32 s2, s2, s73
	s_cmpk_gt_i32 s6, 0x7ff
	s_cbranch_scc0 .LBB0_181

; __device__ __forceinline__ float bflo(unsigned w) { return __uint_as_float(w << 16); }
; __device__ __forceinline__ float bfhi(unsigned w) { return __uint_as_float(w & 0xffff0000u); }
; #define NORM_B_LOAD_MOD(b) f32x4 scv[2][2], shv[2][2]; _Pragma("unroll") for (int j = 0; j < 2; ++j) _Pragma("unroll") for (int n = 0; n < 2; ++n) { \
;         scv[j][n] = *(const f32x4*)(scale + (size_t)(b) * 6144 + 8 * lane + 512 * j + 4 * n) + 1.0f; shv[j][n] = *(const f32x4*)(shift + (size_t)(b) * 6144 + 8 * lane + 512 * j + 4 * n); }
; template <int R>
; __device__ __forceinline__ void norm_rows_b(const bf16* xrow, bf16* hrow, const f32x4 (&gv)[2][2], const f32x4 (&scv)[2][2], const f32x4 (&shv)[2][2], int lane) {
;     u32x4 w[R][2];
; #pragma unroll
;     for (int q = 0; q < R; ++q)
; #pragma unroll
;         for (int j = 0; j < 2; ++j) w[q][j] = *(const u32x4*)(xrow + (size_t)q * 1024 + 8 * lane + 512 * j);
;     f32x4 v[R][2][2]; float ssq[R];
; #pragma unroll
;     for (int q = 0; q < R; ++q) { float s_ = 0.f;
; #pragma unroll
;         for (int j = 0; j < 2; ++j) { const u32x4 ww = w[q][j];
;             v[q][j][0] = (f32x4){bflo(ww.x), bfhi(ww.x), bflo(ww.y), bfhi(ww.y)}; v[q][j][1] = (f32x4){bflo(ww.z), bfhi(ww.z), bflo(ww.w), bfhi(ww.w)};
; #pragma unroll
;             for (int n = 0; n < 2; ++n) s_ += (v[q][j][n].x * v[q][j][n].x + v[q][j][n].y * v[q][j][n].y) + (v[q][j][n].z * v[q][j][n].z + v[q][j][n].w * v[q][j][n].w); }
;         ssq[q] = s_; }
; __device__ __forceinline__ void norm_panels(const bf16* xb, const float* gain, const float* shift, const float* scale, bf16* H, int bid, int G) {
;     ...
;     for (int pm = bid; pm < 256; pm += G) {
;         NORM_B_LOAD_MOD(pm >> 3)
;         const int row0 = pm * 256 + wave * 32;
;         for (int r = 0; r < 32; r += 4) norm_rows_b<4>(xb + (size_t)(row0 + r) * 1024, H + (size_t)(row0 + r) * 1024, gv, scv, shv, lane);
.LBB0_1045:
	s_ashr_i32 s5, s4, 31
	s_lshl_b64 s[0:1], s[4:5], 11
	s_ashr_i32 s5, s6, 3
	v_lshl_add_u64 v[40:41], v[38:39], 0, s[0:1]
	v_mad_i64_i32 v[30:31], s[0:1], s5, v252, v[34:35]
	flat_load_dwordx4 v[18:21], v[30:31]
	v_mad_i64_i32 v[58:59], s[0:1], s5, v252, v[36:37]
	s_mov_b32 s5, -4
	s_mov_b32 s10, 0x358637bd
	s_mov_b64 s[12:13], 0x2000
	s_waitcnt vmcnt(0) lgkmcnt(0)
	v_pk_add_f32 v[42:43], v[20:21], 1.0 op_sel_hi:[1,0]
	v_pk_add_f32 v[44:45], v[18:19], 1.0 op_sel_hi:[1,0]
	flat_load_dwordx4 v[18:21], v[58:59]
	flat_load_dwordx4 v[22:25], v[30:31] offset:16
	s_waitcnt vmcnt(0) lgkmcnt(0)
	v_pk_add_f32 v[46:47], v[24:25], 1.0 op_sel_hi:[1,0]
	v_pk_add_f32 v[48:49], v[22:23], 1.0 op_sel_hi:[1,0]
	flat_load_dwordx4 v[22:25], v[58:59] offset:16
	flat_load_dwordx4 v[26:29], v[30:31] offset:2048
	s_waitcnt vmcnt(0) lgkmcnt(0)
	v_pk_add_f32 v[50:51], v[28:29], 1.0 op_sel_hi:[1,0]
	v_pk_add_f32 v[52:53], v[26:27], 1.0 op_sel_hi:[1,0]
	flat_load_dwordx4 v[26:29], v[58:59] offset:2048
	s_nop 0
	flat_load_dwordx4 v[30:33], v[30:31] offset:2064
	s_waitcnt vmcnt(0) lgkmcnt(0)
	v_pk_add_f32 v[54:55], v[32:33], 1.0 op_sel_hi:[1,0]
	v_pk_add_f32 v[56:57], v[30:31], 1.0 op_sel_hi:[1,0]
	flat_load_dwordx4 v[30:33], v[58:59] offset:2064
	v_add_co_u32_e32 v146, vcc, 0xffffe000, v40
	s_nop 1
	v_addc_co_u32_e32 v147, vcc, -1, v41, vcc
	global_load_dwordx4 v[150:153], v[146:147], off offset:1024
	global_load_dwordx4 v[154:157], v[146:147], off offset:2048
	global_load_dwordx4 v[158:161], v[146:147], off offset:3072
	global_load_dwordx4 v[162:165], v[40:41], off offset:-4096
	global_load_dwordx4 v[166:169], v[40:41], off offset:-3072
	global_load_dwordx4 v[170:173], v[40:41], off offset:-2048
	global_load_dwordx4 v[174:177], v[40:41], off offset:-1024
	global_load_dwordx4 v[178:181], v[40:41], off
	s_waitcnt vmcnt(0) lgkmcnt(0)
.LBB0_1046:
	v_mov_b64_e32 v[58:59], v[150:151]
	v_mov_b64_e32 v[60:61], v[152:153]
	v_mov_b64_e32 v[62:63], v[154:155]
	v_mov_b64_e32 v[64:65], v[156:157]
	v_mov_b64_e32 v[66:67], v[158:159]
	v_mov_b64_e32 v[68:69], v[160:161]
	v_mov_b64_e32 v[70:71], v[162:163]
	v_mov_b64_e32 v[72:73], v[164:165]
	v_mov_b64_e32 v[74:75], v[166:167]
	v_mov_b64_e32 v[76:77], v[168:169]
	v_mov_b64_e32 v[90:91], v[170:171]
	v_mov_b64_e32 v[92:93], v[172:173]
	v_mov_b64_e32 v[126:127], v[174:175]
	v_mov_b64_e32 v[128:129], v[176:177]
	v_mov_b64_e32 v[136:137], v[178:179]
	v_mov_b64_e32 v[138:139], v[180:181]
	s_cmp_gt_i32 s5, 23
	s_cbranch_scc1 .Lnp_skip_1046
	v_lshl_add_u64 v[146:147], v[40:41], 0, s[12:13]
	global_load_dwordx4 v[150:153], v[40:41], off offset:1024
	global_load_dwordx4 v[154:157], v[40:41], off offset:2048
	global_load_dwordx4 v[158:161], v[40:41], off offset:3072
	global_load_dwordx4 v[162:165], v[146:147], off offset:-4096
	global_load_dwordx4 v[166:169], v[146:147], off offset:-3072
	global_load_dwordx4 v[170:173], v[146:147], off offset:-2048
	global_load_dwordx4 v[174:177], v[146:147], off offset:-1024
	global_load_dwordx4 v[178:181], v[146:147], off
.Lnp_skip_1046:
	s_add_i32 s5, s5, 4
	s_cmp_gt_u32 s5, 27
	v_lshlrev_b32_e32 v120, 16, v58
	v_and_b32_e32 v121, 0xffff0000, v58
	v_mul_f32_e32 v0, v120, v120
	v_lshlrev_b32_e32 v124, 16, v59
	v_and_b32_e32 v125, 0xffff0000, v59
	v_pk_fma_f32 v[78:79], v[120:121], v[120:121], v[0:1] op_sel_hi:[1,1,0]
	v_mul_f32_e32 v0, v124, v124
	v_and_b32_e32 v123, 0xffff0000, v61
	v_and_b32_e32 v122, 0xffff0000, v60
	v_lshlrev_b32_e32 v114, 16, v62
	v_pk_fma_f32 v[58:59], v[124:125], v[124:125], v[0:1] op_sel_hi:[1,1,0]
	v_lshlrev_b32_e32 v119, 16, v61
	v_lshlrev_b32_e32 v118, 16, v60
	v_pk_mul_f32 v[60:61], v[122:123], v[122:123]
	v_and_b32_e32 v115, 0xffff0000, v62
	v_mul_f32_e32 v0, v114, v114
	v_lshlrev_b32_e32 v116, 16, v63
	v_pk_fma_f32 v[60:61], v[118:119], v[118:119], v[60:61]
	v_lshlrev_b32_e32 v110, 16, v64
	v_and_b32_e32 v111, 0xffff0000, v64
	v_lshlrev_b32_e32 v112, 16, v65
	v_and_b32_e32 v113, 0xffff0000, v65
	v_pk_fma_f32 v[64:65], v[114:115], v[114:115], v[0:1] op_sel_hi:[1,1,0]
	v_and_b32_e32 v117, 0xffff0000, v63
	v_mul_f32_e32 v0, v116, v116
	v_pk_add_f32 v[60:61], v[60:61], v[60:61] op_sel_hi:[0,1]
	v_pk_fma_f32 v[62:63], v[116:117], v[116:117], v[0:1] op_sel_hi:[1,1,0]
	v_pk_add_f32 v[58:59], v[78:79], v[58:59]
	v_mul_f32_e32 v60, v111, v111
	v_mul_f32_e32 v64, v112, v112
	v_mul_f32_e32 v62, v113, v113
	v_mul_f32_e32 v80, v110, v110
	v_mov_b32_e32 v81, v59
	v_pk_add_f32 v[58:59], v[80:81], v[60:61]
	v_pk_add_f32 v[60:61], v[64:65], v[62:63]
	v_lshlrev_b32_e32 v104, 16, v66
	v_and_b32_e32 v105, 0xffff0000, v66
	v_mul_f32_e32 v0, v104, v104
	v_lshlrev_b32_e32 v108, 16, v67
	v_pk_add_f32 v[140:141], v[58:59], v[60:61]
	v_pk_fma_f32 v[58:59], v[104:105], v[104:105], v[0:1] op_sel_hi:[1,1,0]
	v_and_b32_e32 v109, 0xffff0000, v67
	v_mul_f32_e32 v0, v108, v108
	v_and_b32_e32 v107, 0xffff0000, v69
	v_and_b32_e32 v106, 0xffff0000, v68
	v_lshlrev_b32_e32 v98, 16, v70
	v_pk_fma_f32 v[60:61], v[108:109], v[108:109], v[0:1] op_sel_hi:[1,1,0]
	v_lshlrev_b32_e32 v103, 16, v69
	v_lshlrev_b32_e32 v102, 16, v68
	v_pk_mul_f32 v[62:63], v[106:107], v[106:107]
	v_and_b32_e32 v99, 0xffff0000, v70
	v_mul_f32_e32 v0, v98, v98
	v_lshlrev_b32_e32 v100, 16, v71
	v_pk_fma_f32 v[62:63], v[102:103], v[102:103], v[62:63]
	v_pk_fma_f32 v[64:65], v[98:99], v[98:99], v[0:1] op_sel_hi:[1,1,0]
	v_and_b32_e32 v101, 0xffff0000, v71
	v_mul_f32_e32 v0, v100, v100
	v_pk_add_f32 v[62:63], v[62:63], v[62:63] op_sel_hi:[0,1]
	v_lshlrev_b32_e32 v94, 16, v72
	v_and_b32_e32 v95, 0xffff0000, v72
	v_lshlrev_b32_e32 v96, 16, v73
	v_and_b32_e32 v97, 0xffff0000, v73
	v_pk_fma_f32 v[66:67], v[100:101], v[100:101], v[0:1] op_sel_hi:[1,1,0]
; __device__ __forceinline__ float shx(float v, int m, int lane) { return __int_as_float(__builtin_amdgcn_ds_bpermute((lane ^ m) << 2, __float_as_int(v))); }
; __device__ __forceinline__ float bflo(unsigned w) { return __uint_as_float(w << 16); }
; __device__ __forceinline__ float bfhi(unsigned w) { return __uint_as_float(w & 0xffff0000u); }
; template <int R>
; __device__ __forceinline__ void norm_rows_b(const bf16* xrow, bf16* hrow, const f32x4 (&gv)[2][2], const f32x4 (&scv)[2][2], const f32x4 (&shv)[2][2], int lane) {
;     ...
;     for (int q = 0; q < R; ++q) { float s_ = 0.f;
; #pragma unroll
;         for (int j = 0; j < 2; ++j) { const u32x4 ww = w[q][j];
;             v[q][j][0] = (f32x4){bflo(ww.x), bfhi(ww.x), bflo(ww.y), bfhi(ww.y)}; v[q][j][1] = (f32x4){bflo(ww.z), bfhi(ww.z), bflo(ww.w), bfhi(ww.w)};
; #pragma unroll
;             for (int n = 0; n < 2; ++n) s_ += (v[q][j][n].x * v[q][j][n].x + v[q][j][n].y * v[q][j][n].y) + (v[q][j][n].z * v[q][j][n].z + v[q][j][n].w * v[q][j][n].w); }
;         ssq[q] = s_; }
; #pragma unroll
;     for (int o = 1; o < 64; o <<= 1)
; #pragma unroll
;         for (int q = 0; q < R; ++q) ssq[q] += shx(ssq[q], o, lane);
; #pragma unroll
;     for (int q = 0; q < R; ++q) { const float rstd = rsqrtf(ssq[q] * (1.0f / 1024.0f) + RMS_EPS);
	v_pk_add_f32 v[58:59], v[58:59], v[60:61]
	v_mul_f32_e32 v62, v95, v95
	v_mul_f32_e32 v64, v96, v96
	v_mul_f32_e32 v66, v97, v97
	v_mul_f32_e32 v68, v94, v94
	v_mov_b32_e32 v69, v59
	v_lshlrev_b32_e32 v84, 16, v74
	v_pk_add_f32 v[58:59], v[68:69], v[62:63]
	v_pk_add_f32 v[60:61], v[64:65], v[66:67]
	v_and_b32_e32 v85, 0xffff0000, v74
	v_mul_f32_e32 v0, v84, v84
	v_lshlrev_b32_e32 v88, 16, v75
	v_and_b32_e32 v87, 0xffff0000, v77
	v_and_b32_e32 v86, 0xffff0000, v76
	v_pk_add_f32 v[142:143], v[58:59], v[60:61]
	v_pk_fma_f32 v[58:59], v[84:85], v[84:85], v[0:1] op_sel_hi:[1,1,0]
	v_and_b32_e32 v89, 0xffff0000, v75
	v_mul_f32_e32 v0, v88, v88
	v_lshlrev_b32_e32 v83, 16, v77
	v_lshlrev_b32_e32 v82, 16, v76
	v_pk_mul_f32 v[62:63], v[86:87], v[86:87]
	v_lshlrev_b32_e32 v78, 16, v90
	v_pk_fma_f32 v[60:61], v[88:89], v[88:89], v[0:1] op_sel_hi:[1,1,0]
	v_pk_fma_f32 v[62:63], v[82:83], v[82:83], v[62:63]
	v_and_b32_e32 v79, 0xffff0000, v90
	v_mul_f32_e32 v0, v78, v78
	v_lshlrev_b32_e32 v80, 16, v91
	v_pk_add_f32 v[62:63], v[62:63], v[62:63] op_sel_hi:[0,1]
	v_lshlrev_b32_e32 v74, 16, v92
	v_and_b32_e32 v75, 0xffff0000, v92
	v_pk_fma_f32 v[64:65], v[78:79], v[78:79], v[0:1] op_sel_hi:[1,1,0]
	v_and_b32_e32 v81, 0xffff0000, v91
	v_mul_f32_e32 v0, v80, v80
	v_pk_add_f32 v[58:59], v[58:59], v[60:61]
	v_lshlrev_b32_e32 v76, 16, v93
	v_and_b32_e32 v77, 0xffff0000, v93
	v_pk_fma_f32 v[66:67], v[80:81], v[80:81], v[0:1] op_sel_hi:[1,1,0]
	v_mul_f32_e32 v62, v75, v75
	v_mul_f32_e32 v68, v74, v74
	v_mov_b32_e32 v69, v59
	v_mul_f32_e32 v64, v76, v76
	v_mul_f32_e32 v66, v77, v77
	v_pk_add_f32 v[58:59], v[68:69], v[62:63]
	v_lshlrev_b32_e32 v68, 16, v126
	v_pk_add_f32 v[60:61], v[64:65], v[66:67]
	v_and_b32_e32 v69, 0xffff0000, v126
	v_mul_f32_e32 v0, v68, v68
	v_lshlrev_b32_e32 v72, 16, v127
	v_and_b32_e32 v71, 0xffff0000, v129
	v_and_b32_e32 v70, 0xffff0000, v128
	v_pk_add_f32 v[90:91], v[58:59], v[60:61]
	v_pk_fma_f32 v[92:93], v[68:69], v[68:69], v[0:1] op_sel_hi:[1,1,0]
	v_and_b32_e32 v73, 0xffff0000, v127
	v_mul_f32_e32 v0, v72, v72
	v_lshlrev_b32_e32 v67, 16, v129
	v_lshlrev_b32_e32 v66, 16, v128
	v_pk_mul_f32 v[58:59], v[70:71], v[70:71]
	v_lshlrev_b32_e32 v62, 16, v136
	v_pk_fma_f32 v[126:127], v[72:73], v[72:73], v[0:1] op_sel_hi:[1,1,0]
	v_pk_fma_f32 v[58:59], v[66:67], v[66:67], v[58:59]
	v_and_b32_e32 v63, 0xffff0000, v136
	v_mul_f32_e32 v0, v62, v62
	v_lshlrev_b32_e32 v64, 16, v137
	v_pk_add_f32 v[128:129], v[58:59], v[58:59] op_sel_hi:[0,1]
	v_lshlrev_b32_e32 v58, 16, v138
	v_and_b32_e32 v59, 0xffff0000, v138
	v_lshlrev_b32_e32 v60, 16, v139
	v_and_b32_e32 v61, 0xffff0000, v139
	v_pk_fma_f32 v[138:139], v[62:63], v[62:63], v[0:1] op_sel_hi:[1,1,0]
	v_and_b32_e32 v65, 0xffff0000, v137
	v_mul_f32_e32 v0, v64, v64
	v_pk_fma_f32 v[136:137], v[64:65], v[64:65], v[0:1] op_sel_hi:[1,1,0]
	v_pk_add_f32 v[92:93], v[92:93], v[126:127]
	v_mul_f32_e32 v128, v59, v59
	v_mul_f32_e32 v138, v60, v60
	v_mul_f32_e32 v136, v61, v61
	v_mul_f32_e32 v144, v58, v58
	v_mov_b32_e32 v145, v93
	v_pk_add_f32 v[92:93], v[144:145], v[128:129]
	v_pk_add_f32 v[126:127], v[138:139], v[136:137]
	v_mov_b32_e32 v136, v119
	v_pk_add_f32 v[92:93], v[92:93], v[126:127]
	v_mov_b32_e32 v126, v142
	v_mov_b32_e32 v127, v140
	v_mov_b32_e32 v140, v143
	v_pk_add_f32 v[126:127], v[126:127], v[140:141]
	ds_bpermute_b32 v129, v130, v127
	ds_bpermute_b32 v128, v130, v126
	v_mov_b32_e32 v137, v123
	v_mov_b32_e32 v119, v122
	s_waitcnt lgkmcnt(0)
	v_pk_add_f32 v[126:127], v[126:127], v[128:129]
	ds_bpermute_b32 v129, v131, v127
	ds_bpermute_b32 v128, v131, v126
	s_waitcnt lgkmcnt(0)
	v_pk_add_f32 v[126:127], v[126:127], v[128:129]
	ds_bpermute_b32 v129, v132, v127
	ds_bpermute_b32 v128, v132, v126
	s_waitcnt lgkmcnt(0)
	v_pk_add_f32 v[126:127], v[126:127], v[128:129]
	ds_bpermute_b32 v129, v133, v127
	ds_bpermute_b32 v128, v133, v126
	s_waitcnt lgkmcnt(0)
	v_pk_add_f32 v[126:127], v[126:127], v[128:129]
	ds_bpermute_b32 v129, v134, v127
	ds_bpermute_b32 v128, v134, v126
	s_waitcnt lgkmcnt(0)
	v_pk_add_f32 v[126:127], v[126:127], v[128:129]
	ds_bpermute_b32 v129, v135, v127
	ds_bpermute_b32 v128, v135, v126
	s_waitcnt lgkmcnt(0)
	v_pk_add_f32 v[126:127], v[126:127], v[128:129]
	v_mov_b64_e32 v[128:129], s[10:11]
	v_pk_fma_f32 v[126:127], v[126:127], s[86:87], v[128:129] op_sel_hi:[1,0,0]
	s_nop 0
	v_mul_f32_e32 v0, 0x4b800000, v127
	v_cmp_gt_f32_e64 s[0:1], s87, v127
	v_cmp_gt_f32_e32 vcc, s87, v126
	s_nop 0
	v_cndmask_b32_e64 v0, v127, v0, s[0:1]
	v_rsq_f32_e32 v0, v0
	s_nop 0
	v_mul_f32_e32 v127, 0x45800000, v0
	v_cndmask_b32_e64 v0, v0, v127, s[0:1]
	v_pk_mul_f32 v[120:121], v[0:1], v[120:121] op_sel_hi:[0,1]
	v_pk_mul_f32 v[136:137], v[0:1], v[136:137] op_sel_hi:[0,1]
	v_pk_mul_f32 v[124:125], v[0:1], v[124:125] op_sel_hi:[0,1]
	v_pk_mul_f32 v[120:121], v[6:7], v[120:121]
	v_pk_mul_f32 v[118:119], v[0:1], v[118:119] op_sel_hi:[0,1]
	v_pk_mul_f32 v[122:123], v[4:5], v[136:137]
	v_pk_mul_f32 v[116:117], v[0:1], v[116:117] op_sel_hi:[0,1]
	v_pk_mul_f32 v[114:115], v[0:1], v[114:115] op_sel_hi:[0,1]
	v_pk_mul_f32 v[112:113], v[0:1], v[112:113] op_sel_hi:[0,1]
	v_pk_mul_f32 v[110:111], v[0:1], v[110:111] op_sel_hi:[0,1]
	v_mul_f32_e32 v0, 0x4b800000, v126
	v_pk_mul_f32 v[124:125], v[8:9], v[124:125]
	v_pk_fma_f32 v[120:121], v[44:45], v[120:121], v[18:19]
	v_pk_mul_f32 v[118:119], v[2:3], v[118:119]
	v_pk_fma_f32 v[122:123], v[46:47], v[122:123], v[24:25]
	v_cndmask_b32_e32 v0, v126, v0, vcc
	v_pk_fma_f32 v[124:125], v[42:43], v[124:125], v[20:21]
	v_pk_fma_f32 v[136:137], v[48:49], v[118:119], v[22:23]
	v_cvt_pk_bf16_f32 v118, v120, v121
	v_cvt_pk_bf16_f32 v121, v122, v123
	v_add_co_u32_e64 v122, s[0:1], s77, v40
; __device__ __forceinline__ unsigned cvt_pk_bf16(float lo, float hi) { f32x2_t v = {lo, hi}; bf16x2_t b = __builtin_convertvector(v, bf16x2_t); return __builtin_bit_cast(unsigned, b); }
; template <int R>
; __device__ __forceinline__ void norm_rows_b(const bf16* xrow, bf16* hrow, const f32x4 (&gv)[2][2], const f32x4 (&scv)[2][2], const f32x4 (&shv)[2][2], int lane) {
;     ...
;     for (int q = 0; q < R; ++q) { const float rstd = rsqrtf(ssq[q] * (1.0f / 1024.0f) + RMS_EPS);
; #pragma unroll
;         for (int j = 0; j < 2; ++j) { const f32x4 y0 = v[q][j][0] * rstd * gv[j][0] * scv[j][0] + shv[j][0], y1 = v[q][j][1] * rstd * gv[j][1] * scv[j][1] + shv[j][1];
;             u32x4 o_; o_.x = cvt_pk_bf16(y0.x, y0.y); o_.y = cvt_pk_bf16(y0.z, y0.w); o_.z = cvt_pk_bf16(y1.x, y1.y); o_.w = cvt_pk_bf16(y1.z, y1.w);
;             *(u32x4*)(hrow + (size_t)q * 1024 + 8 * lane + 512 * j) = o_; } }
	v_pk_mul_f32 v[114:115], v[14:15], v[114:115]
	v_rsq_f32_e32 v0, v0
	v_cvt_pk_bf16_f32 v119, v124, v125
	v_cvt_pk_bf16_f32 v120, v136, v137
	v_addc_co_u32_e64 v123, s[0:1], -1, v41, s[0:1]
	v_pk_mul_f32 v[116:117], v[16:17], v[116:117]
	v_pk_fma_f32 v[114:115], v[52:53], v[114:115], v[26:27]
	v_pk_mul_f32 v[110:111], v[10:11], v[110:111]
	v_pk_mul_f32 v[112:113], v[12:13], v[112:113]
	global_store_dwordx4 v[122:123], v[118:121], off
	v_pk_fma_f32 v[116:117], v[50:51], v[116:117], v[28:29]
	s_nop 0
	v_pk_fma_f32 v[118:119], v[54:55], v[112:113], v[32:33]
	v_pk_fma_f32 v[112:113], v[56:57], v[110:111], v[30:31]
	v_cvt_pk_bf16_f32 v110, v114, v115
	v_add_co_u32_e64 v114, s[0:1], s92, v40
	v_cvt_pk_bf16_f32 v111, v116, v117
	v_cvt_pk_bf16_f32 v112, v112, v113
	v_cvt_pk_bf16_f32 v113, v118, v119
	v_addc_co_u32_e64 v115, s[0:1], -1, v41, s[0:1]
	global_store_dwordx4 v[114:115], v[110:113], off
	s_nop 1
	v_mul_f32_e32 v110, 0x45800000, v0
	v_cndmask_b32_e32 v0, v0, v110, vcc
	v_mov_b32_e32 v110, v103
	v_mov_b32_e32 v111, v107
	v_pk_mul_f32 v[104:105], v[0:1], v[104:105] op_sel_hi:[0,1]
	v_pk_mul_f32 v[110:111], v[0:1], v[110:111] op_sel_hi:[0,1]
	v_mov_b32_e32 v103, v106
	v_pk_mul_f32 v[108:109], v[0:1], v[108:109] op_sel_hi:[0,1]
	v_pk_mul_f32 v[104:105], v[6:7], v[104:105]
	v_pk_mul_f32 v[102:103], v[0:1], v[102:103] op_sel_hi:[0,1]
	v_pk_mul_f32 v[106:107], v[4:5], v[110:111]
	v_pk_mul_f32 v[108:109], v[8:9], v[108:109]
	v_pk_fma_f32 v[104:105], v[44:45], v[104:105], v[18:19]
	v_pk_mul_f32 v[102:103], v[2:3], v[102:103]
	v_pk_fma_f32 v[106:107], v[46:47], v[106:107], v[24:25]
	v_pk_mul_f32 v[98:99], v[0:1], v[98:99] op_sel_hi:[0,1]
	v_pk_fma_f32 v[108:109], v[42:43], v[108:109], v[20:21]
	v_pk_fma_f32 v[110:111], v[48:49], v[102:103], v[22:23]
	v_cvt_pk_bf16_f32 v102, v104, v105
	v_cvt_pk_bf16_f32 v105, v106, v107
	v_add_co_u32_e32 v106, vcc, s93, v40
	v_pk_mul_f32 v[100:101], v[0:1], v[100:101] op_sel_hi:[0,1]
	v_pk_mul_f32 v[98:99], v[14:15], v[98:99]
	v_pk_mul_f32 v[96:97], v[0:1], v[96:97] op_sel_hi:[0,1]
	v_pk_mul_f32 v[94:95], v[0:1], v[94:95] op_sel_hi:[0,1]
	v_cvt_pk_bf16_f32 v103, v108, v109
	v_cvt_pk_bf16_f32 v104, v110, v111
	v_addc_co_u32_e32 v107, vcc, -1, v41, vcc
	v_pk_mul_f32 v[100:101], v[16:17], v[100:101]
	v_pk_fma_f32 v[98:99], v[52:53], v[98:99], v[26:27]
	v_pk_mul_f32 v[94:95], v[10:11], v[94:95]
	v_pk_mul_f32 v[96:97], v[12:13], v[96:97]
	global_store_dwordx4 v[106:107], v[102:105], off
	v_pk_fma_f32 v[100:101], v[50:51], v[100:101], v[28:29]
	s_nop 0
	v_pk_fma_f32 v[102:103], v[54:55], v[96:97], v[32:33]
	v_pk_fma_f32 v[96:97], v[56:57], v[94:95], v[30:31]
	v_cvt_pk_bf16_f32 v94, v98, v99
	v_add_co_u32_e32 v98, vcc, s66, v40
	v_cvt_pk_bf16_f32 v95, v100, v101
	v_cvt_pk_bf16_f32 v96, v96, v97
	v_cvt_pk_bf16_f32 v97, v102, v103
	v_addc_co_u32_e32 v99, vcc, -1, v41, vcc
	global_store_dwordx4 v[98:99], v[94:97], off
	s_nop 1
	v_mov_b32_e32 v94, v92
	v_mov_b32_e32 v95, v90
	v_mov_b32_e32 v90, v93
	v_pk_add_f32 v[90:91], v[94:95], v[90:91]
	ds_bpermute_b32 v93, v130, v91
	ds_bpermute_b32 v92, v130, v90
	s_waitcnt lgkmcnt(0)
	v_pk_add_f32 v[90:91], v[90:91], v[92:93]
	ds_bpermute_b32 v93, v131, v91
	ds_bpermute_b32 v92, v131, v90
	s_waitcnt lgkmcnt(0)
	v_pk_add_f32 v[90:91], v[90:91], v[92:93]
	ds_bpermute_b32 v93, v132, v91
	ds_bpermute_b32 v92, v132, v90
	s_waitcnt lgkmcnt(0)
	v_pk_add_f32 v[90:91], v[90:91], v[92:93]
	ds_bpermute_b32 v93, v133, v91
	ds_bpermute_b32 v92, v133, v90
	s_waitcnt lgkmcnt(0)
	v_pk_add_f32 v[90:91], v[90:91], v[92:93]
	ds_bpermute_b32 v93, v134, v91
	ds_bpermute_b32 v92, v134, v90
	s_waitcnt lgkmcnt(0)
	v_pk_add_f32 v[90:91], v[90:91], v[92:93]
	ds_bpermute_b32 v93, v135, v91
	ds_bpermute_b32 v92, v135, v90
	s_waitcnt lgkmcnt(0)
; __device__ __forceinline__ unsigned cvt_pk_bf16(float lo, float hi) { f32x2_t v = {lo, hi}; bf16x2_t b = __builtin_convertvector(v, bf16x2_t); return __builtin_bit_cast(unsigned, b); }
; #define NORM_B_LOAD_MOD(b) f32x4 scv[2][2], shv[2][2]; _Pragma("unroll") for (int j = 0; j < 2; ++j) _Pragma("unroll") for (int n = 0; n < 2; ++n) { \
;         scv[j][n] = *(const f32x4*)(scale + (size_t)(b) * 6144 + 8 * lane + 512 * j + 4 * n) + 1.0f; shv[j][n] = *(const f32x4*)(shift + (size_t)(b) * 6144 + 8 * lane + 512 * j + 4 * n); }
; template <int R>
; __device__ __forceinline__ void norm_rows_b(const bf16* xrow, bf16* hrow, const f32x4 (&gv)[2][2], const f32x4 (&scv)[2][2], const f32x4 (&shv)[2][2], int lane) {
;     ...
;     for (int q = 0; q < R; ++q) { const float rstd = rsqrtf(ssq[q] * (1.0f / 1024.0f) + RMS_EPS);
; #pragma unroll
;         for (int j = 0; j < 2; ++j) { const f32x4 y0 = v[q][j][0] * rstd * gv[j][0] * scv[j][0] + shv[j][0], y1 = v[q][j][1] * rstd * gv[j][1] * scv[j][1] + shv[j][1];
;             u32x4 o_; o_.x = cvt_pk_bf16(y0.x, y0.y); o_.y = cvt_pk_bf16(y0.z, y0.w); o_.z = cvt_pk_bf16(y1.x, y1.y); o_.w = cvt_pk_bf16(y1.z, y1.w);
;             *(u32x4*)(hrow + (size_t)q * 1024 + 8 * lane + 512 * j) = o_; } }
; __device__ __forceinline__ void norm_panels(const bf16* xb, const float* gain, const float* shift, const float* scale, bf16* H, int bid, int G) {
;     ...
;     for (int pm = bid; pm < 256; pm += G) {
;         NORM_B_LOAD_MOD(pm >> 3)
;         const int row0 = pm * 256 + wave * 32;
;         for (int r = 0; r < 32; r += 4) norm_rows_b<4>(xb + (size_t)(row0 + r) * 1024, H + (size_t)(row0 + r) * 1024, gv, scv, shv, lane);
	v_pk_add_f32 v[90:91], v[90:91], v[92:93]
	s_nop 0
	v_pk_fma_f32 v[90:91], v[90:91], s[86:87], v[128:129] op_sel_hi:[1,0,0]
	v_mov_b32_e32 v92, v83
	v_mul_f32_e32 v0, 0x4b800000, v91
	v_cmp_gt_f32_e64 s[0:1], s87, v91
	v_mov_b32_e32 v93, v87
	v_mov_b32_e32 v83, v86
	v_cndmask_b32_e64 v0, v91, v0, s[0:1]
	v_rsq_f32_e32 v0, v0
	v_cmp_gt_f32_e32 vcc, s87, v90
	v_mul_f32_e32 v91, 0x45800000, v0
	v_cndmask_b32_e64 v0, v0, v91, s[0:1]
	v_pk_mul_f32 v[84:85], v[0:1], v[84:85] op_sel_hi:[0,1]
	v_pk_mul_f32 v[92:93], v[0:1], v[92:93] op_sel_hi:[0,1]
	v_pk_mul_f32 v[88:89], v[0:1], v[88:89] op_sel_hi:[0,1]
	v_pk_mul_f32 v[84:85], v[6:7], v[84:85]
	v_pk_mul_f32 v[82:83], v[0:1], v[82:83] op_sel_hi:[0,1]
	v_pk_mul_f32 v[86:87], v[4:5], v[92:93]
	v_pk_mul_f32 v[80:81], v[0:1], v[80:81] op_sel_hi:[0,1]
	v_pk_mul_f32 v[78:79], v[0:1], v[78:79] op_sel_hi:[0,1]
	v_pk_mul_f32 v[76:77], v[0:1], v[76:77] op_sel_hi:[0,1]
	v_pk_mul_f32 v[74:75], v[0:1], v[74:75] op_sel_hi:[0,1]
	v_mul_f32_e32 v0, 0x4b800000, v90
	v_pk_mul_f32 v[88:89], v[8:9], v[88:89]
	v_pk_fma_f32 v[84:85], v[44:45], v[84:85], v[18:19]
	v_pk_mul_f32 v[82:83], v[2:3], v[82:83]
	v_pk_fma_f32 v[86:87], v[46:47], v[86:87], v[24:25]
	v_cndmask_b32_e32 v0, v90, v0, vcc
	v_pk_fma_f32 v[88:89], v[42:43], v[88:89], v[20:21]
	v_pk_fma_f32 v[92:93], v[48:49], v[82:83], v[22:23]
	v_cvt_pk_bf16_f32 v82, v84, v85
	v_cvt_pk_bf16_f32 v85, v86, v87
	v_add_co_u32_e64 v86, s[0:1], s67, v40
	v_pk_mul_f32 v[78:79], v[14:15], v[78:79]
	v_rsq_f32_e32 v0, v0
	v_cvt_pk_bf16_f32 v83, v88, v89
	v_cvt_pk_bf16_f32 v84, v92, v93
	v_addc_co_u32_e64 v87, s[0:1], -1, v41, s[0:1]
	v_pk_mul_f32 v[80:81], v[16:17], v[80:81]
	v_pk_fma_f32 v[78:79], v[52:53], v[78:79], v[26:27]
	v_pk_mul_f32 v[74:75], v[10:11], v[74:75]
	v_pk_mul_f32 v[76:77], v[12:13], v[76:77]
	global_store_dwordx4 v[86:87], v[82:85], off
	v_pk_fma_f32 v[80:81], v[50:51], v[80:81], v[28:29]
	s_nop 0
	v_pk_fma_f32 v[82:83], v[54:55], v[76:77], v[32:33]
	v_pk_fma_f32 v[76:77], v[56:57], v[74:75], v[30:31]
	v_cvt_pk_bf16_f32 v74, v78, v79
	v_add_co_u32_e64 v78, s[0:1], s7, v40
	v_cvt_pk_bf16_f32 v75, v80, v81
	v_cvt_pk_bf16_f32 v76, v76, v77
	v_cvt_pk_bf16_f32 v77, v82, v83
	v_addc_co_u32_e64 v79, s[0:1], -1, v41, s[0:1]
	global_store_dwordx4 v[78:79], v[74:77], off
	s_nop 1
	v_mul_f32_e32 v74, 0x45800000, v0
	v_cndmask_b32_e32 v0, v0, v74, vcc
	v_mov_b32_e32 v74, v67
	v_mov_b32_e32 v75, v71
	v_pk_mul_f32 v[68:69], v[0:1], v[68:69] op_sel_hi:[0,1]
	v_pk_mul_f32 v[74:75], v[0:1], v[74:75] op_sel_hi:[0,1]
	v_mov_b32_e32 v67, v70
	v_pk_mul_f32 v[72:73], v[0:1], v[72:73] op_sel_hi:[0,1]
	v_pk_mul_f32 v[68:69], v[6:7], v[68:69]
	v_pk_mul_f32 v[66:67], v[0:1], v[66:67] op_sel_hi:[0,1]
	v_pk_mul_f32 v[70:71], v[4:5], v[74:75]
	v_pk_mul_f32 v[72:73], v[8:9], v[72:73]
	v_pk_fma_f32 v[68:69], v[44:45], v[68:69], v[18:19]
	v_pk_mul_f32 v[66:67], v[2:3], v[66:67]
	v_pk_fma_f32 v[70:71], v[46:47], v[70:71], v[24:25]
	v_pk_mul_f32 v[62:63], v[0:1], v[62:63] op_sel_hi:[0,1]
	v_pk_fma_f32 v[72:73], v[42:43], v[72:73], v[20:21]
	v_pk_fma_f32 v[74:75], v[48:49], v[66:67], v[22:23]
	v_cvt_pk_bf16_f32 v66, v68, v69
	v_cvt_pk_bf16_f32 v69, v70, v71
	v_add_co_u32_e32 v70, vcc, s8, v40
	v_pk_mul_f32 v[64:65], v[0:1], v[64:65] op_sel_hi:[0,1]
	v_pk_mul_f32 v[62:63], v[14:15], v[62:63]
	v_pk_mul_f32 v[60:61], v[0:1], v[60:61] op_sel_hi:[0,1]
	v_pk_mul_f32 v[58:59], v[0:1], v[58:59] op_sel_hi:[0,1]
	v_cvt_pk_bf16_f32 v67, v72, v73
	v_cvt_pk_bf16_f32 v68, v74, v75
	v_addc_co_u32_e32 v71, vcc, -1, v41, vcc
	v_pk_mul_f32 v[64:65], v[16:17], v[64:65]
	v_pk_fma_f32 v[62:63], v[52:53], v[62:63], v[26:27]
	v_pk_mul_f32 v[58:59], v[10:11], v[58:59]
	v_pk_mul_f32 v[60:61], v[12:13], v[60:61]
	global_store_dwordx4 v[70:71], v[66:69], off
	v_pk_fma_f32 v[64:65], v[50:51], v[64:65], v[28:29]
	s_nop 0
	v_pk_fma_f32 v[66:67], v[54:55], v[60:61], v[32:33]
	v_pk_fma_f32 v[60:61], v[56:57], v[58:59], v[30:31]
	v_cvt_pk_bf16_f32 v58, v62, v63
	v_add_co_u32_e32 v62, vcc, 0xd7800000, v40
	v_cvt_pk_bf16_f32 v59, v64, v65
	v_cvt_pk_bf16_f32 v60, v60, v61
	v_cvt_pk_bf16_f32 v61, v66, v67
	v_addc_co_u32_e32 v63, vcc, -1, v41, vcc
	v_lshl_add_u64 v[40:41], v[40:41], 0, s[12:13]
	global_store_dwordx4 v[62:63], v[58:61], off
	s_waitcnt vmcnt(8)
	s_cbranch_scc0 .LBB0_1046
	s_add_i32 s6, s6, s74
	s_add_i32 s4, s4, s73
	s_cmpk_gt_i32 s6, 0xff
	s_cbranch_scc0 .LBB0_1045
	s_brev_b32 s80, 4
